# grid-barrier XCC-count init moved into the P0|P1 seam wait (off the P2|P3 barrier's critical path)
# baseline (speedup 1.0000x reference)
; __device__ __forceinline__ unsigned xb_ld(unsigned* p)              { return __hip_atomic_load(p, __ATOMIC_RELAXED, __HIP_MEMORY_SCOPE_AGENT); }
; __device__ __forceinline__ void xcd_barrier_complete(unsigned* bar, unsigned x, unsigned& nloc, unsigned& nx) {
;     const unsigned G = gridDim.x * gridDim.y * gridDim.z;
;     unsigned sum, cnt, mine, sp = 0u;
;     for (;;) {
;         sum = 0u; cnt = 0u; mine = 0u;
; #pragma unroll
;         for (unsigned j = 0; j < 16; ++j) { const unsigned c = xb_ld(&bar[XB_XCNT(j)]); sum += c; cnt += (c > 0u) ? 1u : 0u; mine = (j == x) ? c : mine; }
;         if (sum == G) break;
;         __builtin_amdgcn_s_sleep(1);
;         if ((++sp & 255u) == 0u) { if (xb_ld(&bar[XB_TMO])) break; if (sp > XB_SPIN_CAP) { atomicAdd(&bar[XB_TMO], 1u); break; } }
;     }
;     nloc = mine > 0u ? mine : 1u; nx = cnt > 0u ? cnt : 1u;
; }
; __device__ __forceinline__ void xcd_barrier(const XcdBarrier& b) {
;     asm volatile("s_waitcnt vmcnt(0)" ::: "memory");
;     __syncthreads();
;     if (threadIdx.x == 0) {
;         unsigned* bar = b.bar;
;         __builtin_amdgcn_s_waitcnt(0);
;         unsigned nloc = b.st[0], nx = b.st[1];
;         if (nloc == 0u) { xcd_barrier_complete(bar, b.x, nloc, nx); b.st[0] = nloc; b.st[1] = nx; }
.LBB0_65:
	s_cmp_gt_i32 s57, 1
	s_barrier
	s_cbranch_scc0 .LBB0_115
	s_waitcnt vmcnt(0)
	s_barrier
	s_and_saveexec_b64 s[6:7], s[96:97]
	s_cbranch_execz .Lts0_join
	s_and_b32 s3, s2, 7
	s_lshl_b32 s3, s3, 3
	s_bfe_u32 s4, s2, 0x30003
	s_or_b32 s3, s3, s4
	s_lshl_b32 s3, s3, 7
	s_add_u32 s8, s60, s3
	s_addc_u32 s9, s61, 0
	s_add_u32 s8, s8, 0x2d000
	s_addc_u32 s9, s9, 0
	v_mov_b32_e32 v1, 0
	v_mov_b32_e32 v2, 1
	v_mov_b32_e32 v3, 0x2c100
	v_mov_b32_e32 v5, 0
	global_atomic_add v1, v2, s[8:9]
	s_add_i32 s3, 0, 0x22960
	v_mov_b32_e32 v1, s3
	s_waitcnt vmcnt(0) expcnt(0) lgkmcnt(0)
	ds_read_b32 v3, v1
	s_add_i32 s3, 0, 0x22964
	v_mov_b32_e32 v1, s3
	ds_read_b32 v1, v1
	s_waitcnt lgkmcnt(1)
	v_cmp_ne_u32_e32 vcc, 0, v3
	s_cbranch_vccnz .LBB0_82
	v_readlane_b32 s8, v240, 0
	v_readlane_b32 s9, v240, 1
	s_load_dwordx2 s[12:13], s[8:9], 0x4
	s_add_u32 s8, s58, 0x1000
	s_addc_u32 s9, s59, 0
	s_add_u32 s10, s58, 0x1100
	s_addc_u32 s11, s59, 0
	s_waitcnt lgkmcnt(0)
	s_mul_i32 s3, s12, s34
	s_add_u32 s12, s58, 0x1200
	s_mul_i32 s3, s3, s13
	s_addc_u32 s13, s59, 0
	s_add_u32 s14, s58, 0x1300
	s_addc_u32 s15, s59, 0
	s_mov_b32 s4, 1
	v_mov_b32_e32 v17, 0
	s_branch .LBB0_70

; __device__ __forceinline__ unsigned xb_ld(unsigned* p)              { return __hip_atomic_load(p, __ATOMIC_RELAXED, __HIP_MEMORY_SCOPE_AGENT); }
; __device__ __forceinline__ void xcd_barrier_complete(unsigned* bar, unsigned x, unsigned& nloc, unsigned& nx) {
;     const unsigned G = gridDim.x * gridDim.y * gridDim.z;
;     unsigned sum, cnt, mine, sp = 0u;
;     for (;;) {
;         sum = 0u; cnt = 0u; mine = 0u;
; #pragma unroll
;         for (unsigned j = 0; j < 16; ++j) { const unsigned c = xb_ld(&bar[XB_XCNT(j)]); sum += c; cnt += (c > 0u) ? 1u : 0u; mine = (j == x) ? c : mine; }
;         if (sum == G) break;
;         __builtin_amdgcn_s_sleep(1);
;         if ((++sp & 255u) == 0u) { if (xb_ld(&bar[XB_TMO])) break; if (sp > XB_SPIN_CAP) { atomicAdd(&bar[XB_TMO], 1u); break; } }
;     }
;     nloc = mine > 0u ? mine : 1u; nx = cnt > 0u ? cnt : 1u;
; }
; __device__ __forceinline__ void xcd_barrier(const XcdBarrier& b) {
;     asm volatile("s_waitcnt vmcnt(0)" ::: "memory");
;     __syncthreads();
;     if (threadIdx.x == 0) {
;         unsigned* bar = b.bar;
;         __builtin_amdgcn_s_waitcnt(0);
;         unsigned nloc = b.st[0], nx = b.st[1];
;         if (nloc == 0u) { xcd_barrier_complete(bar, b.x, nloc, nx); b.st[0] = nloc; b.st[1] = nx; }
.LBB0_82:
	s_and_b32 s3, s2, 7
	s_lshl_b32 s3, s3, 3
	s_bfe_u32 s4, s2, 0x30003
	s_or_b32 s3, s3, s4
	s_lshl_b32 s3, s3, 7
	s_add_u32 s8, s60, s3
	s_addc_u32 s9, s61, 0
	s_add_u32 s8, s8, 0x2d000
	s_addc_u32 s9, s9, 0
	v_mov_b32_e32 v1, 0
	v_mov_b32_e32 v2, 1
	v_mov_b32_e32 v3, 0x2c100
	v_mov_b32_e32 v5, 0
	s_waitcnt lgkmcnt(0)
